# rotK + P0 cache-conversion loops batched: two iterations and both tensors per pass, 8 loads in flight before the first wait (original loop kept for remainders)
# baseline (speedup 1.0000x reference)
; __device__ __forceinline__ unsigned pk2(float lo, float hi) { f32x2_t v = {lo, hi}; bf16x2_t b = __builtin_convertvector(v, bf16x2_t); return __builtin_bit_cast(unsigned, b); }
; __device__ __forceinline__ void conv_chunk(const float* src, bf16_t* dst, int c, int pshift, int L) {
;     const int row = c >> 6, col8 = c & 63, b = row >> pshift, pos = row & ((1 << pshift) - 1);
;     const f32x4 a = *(const f32x4*)(src + (size_t)c * 8), d = *(const f32x4*)(src + (size_t)c * 8 + 4);
;     u32x4 o; o.x = pk2(a[0], a[1]); o.y = pk2(a[2], a[3]); o.z = pk2(d[0], d[1]); o.w = pk2(d[2], d[3]);
;     *(u32x4*)(dst + (((size_t)(b * 8 + (col8 >> 3)) * L + pos) * 64 + (col8 & 7) * 8)) = o;
; }
; __device__ __forceinline__ void phase0(const Params& P, LAS unsigned char* lds, int tid, int lane, int wave) {
;     ...
;     for (int c = gt; c < NSB * LAC * 64; c += NT) { conv_chunk(P.cak, (bf16_t*)(P.ws + WS_KAS), c, 9, LAS_LEN); conv_chunk(P.cav, (bf16_t*)(P.ws + WS_VAS), c, 9, LAS_LEN); }
.Lcva_top:
	v_add_u32_e32 v203, s0, v9
	v_cmp_lt_i32_e32 vcc, s14, v203
	s_nop 1
	s_and_b64 s[16:17], vcc, exec
	s_cbranch_scc1 .LBB0_37
	v_lshl_add_u64 v[204:205], s[72:73], 0, v[4:5]
	global_load_dwordx4 v[146:149], v[204:205], off
	global_load_dwordx4 v[150:153], v[204:205], off offset:16
	v_lshl_add_u64 v[204:205], s[74:75], 0, v[4:5]
	global_load_dwordx4 v[154:157], v[204:205], off
	global_load_dwordx4 v[158:161], v[204:205], off offset:16
	v_lshl_add_u64 v[206:207], v[4:5], 0, s[10:11]
	v_lshl_add_u64 v[204:205], s[72:73], 0, v[206:207]
	global_load_dwordx4 v[162:165], v[204:205], off
	global_load_dwordx4 v[166:169], v[204:205], off offset:16
	v_lshl_add_u64 v[204:205], s[74:75], 0, v[206:207]
	global_load_dwordx4 v[170:173], v[204:205], off
	global_load_dwordx4 v[174:177], v[204:205], off offset:16
	v_ashrrev_i32_e32 v18, 12, v9
	v_bfe_u32 v20, v9, 3, 3
	v_and_or_b32 v18, v18, s1, v20
	v_mul_i32_i24_e32 v18, 0x220, v18
	v_bfe_u32 v6, v9, 6, 9
	v_ashrrev_i32_e32 v19, 31, v18
	v_lshl_add_u64 v[18:19], v[18:19], 0, v[6:7]
	v_lshlrev_b64 v[198:199], 7, v[18:19]
	v_ashrrev_i32_e32 v18, 12, v203
	v_bfe_u32 v20, v203, 3, 3
	v_and_or_b32 v18, v18, s1, v20
	v_mul_i32_i24_e32 v18, 0x220, v18
	v_bfe_u32 v6, v203, 6, 9
	v_ashrrev_i32_e32 v19, 31, v18
	v_lshl_add_u64 v[18:19], v[18:19], 0, v[6:7]
	v_lshlrev_b64 v[200:201], 7, v[18:19]
	v_and_b32_e32 v6, 56, v8
	v_lshlrev_b32_e32 v6, 1, v6
	v_lshl_add_u64 v[198:199], v[198:199], 0, v[6:7]
	v_lshl_add_u64 v[200:201], v[200:201], 0, v[6:7]
	v_add_u32_e32 v9, s0, v203
	v_add_u32_e32 v8, s3, v8
	v_add_u32_e32 v8, s3, v8
	v_lshl_add_u64 v[4:5], v[206:207], 0, s[10:11]
	s_waitcnt vmcnt(6)
	v_cvt_pk_bf16_f32 v146, v146, v147
	v_cvt_pk_bf16_f32 v147, v148, v149
	v_cvt_pk_bf16_f32 v148, v150, v151
	v_cvt_pk_bf16_f32 v149, v152, v153
	v_lshl_add_u64 v[204:205], s[6:7], 0, v[198:199]
	global_store_dwordx4 v[204:205], v[146:149], off
	s_waitcnt vmcnt(5)
	v_cvt_pk_bf16_f32 v154, v154, v155
	v_cvt_pk_bf16_f32 v155, v156, v157
	v_cvt_pk_bf16_f32 v156, v158, v159
	v_cvt_pk_bf16_f32 v157, v160, v161
	v_lshl_add_u64 v[204:205], s[8:9], 0, v[198:199]
	global_store_dwordx4 v[204:205], v[154:157], off
	s_waitcnt vmcnt(4)
	v_cvt_pk_bf16_f32 v162, v162, v163
	v_cvt_pk_bf16_f32 v163, v164, v165
	v_cvt_pk_bf16_f32 v164, v166, v167
	v_cvt_pk_bf16_f32 v165, v168, v169
	v_lshl_add_u64 v[204:205], s[6:7], 0, v[200:201]
	global_store_dwordx4 v[204:205], v[162:165], off
	s_waitcnt vmcnt(3)
	v_cvt_pk_bf16_f32 v170, v170, v171
	v_cvt_pk_bf16_f32 v171, v172, v173
	v_cvt_pk_bf16_f32 v172, v174, v175
	v_cvt_pk_bf16_f32 v173, v176, v177
	v_lshl_add_u64 v[204:205], s[8:9], 0, v[200:201]
	global_store_dwordx4 v[204:205], v[170:173], off
	v_cmp_lt_i32_e32 vcc, s14, v9
	s_nop 1
	s_andn2_b64 s[16:17], exec, vcc
	s_cbranch_scc0 .LBB0_38
	s_mov_b64 exec, s[16:17]
	s_branch .Lcva_top

; __device__ __forceinline__ unsigned pk2(float lo, float hi) { f32x2_t v = {lo, hi}; bf16x2_t b = __builtin_convertvector(v, bf16x2_t); return __builtin_bit_cast(unsigned, b); }
; __device__ __forceinline__ void conv_chunk(const float* src, bf16_t* dst, int c, int pshift, int L) {
;     const int row = c >> 6, col8 = c & 63, b = row >> pshift, pos = row & ((1 << pshift) - 1);
;     const f32x4 a = *(const f32x4*)(src + (size_t)c * 8), d = *(const f32x4*)(src + (size_t)c * 8 + 4);
;     u32x4 o; o.x = pk2(a[0], a[1]); o.y = pk2(a[2], a[3]); o.z = pk2(d[0], d[1]); o.w = pk2(d[2], d[3]);
;     *(u32x4*)(dst + (((size_t)(b * 8 + (col8 >> 3)) * L + pos) * 64 + (col8 & 7) * 8)) = o;
; }
; __device__ __forceinline__ void phase0(const Params& P, LAS unsigned char* lds, int tid, int lane, int wave) {
;     ...
;     for (int c = gt; c < NSB * PAST * 64; c += NT) { conv_chunk(P.cbk, (bf16_t*)(P.ws + WS_KBS), c, 11, LBS_LEN); conv_chunk(P.cbv, (bf16_t*)(P.ws + WS_VBS), c, 11, LBS_LEN); }
.Lcvb_top:
	v_add_u32_e32 v203, s0, v2
	v_cmp_lt_i32_e32 vcc, s14, v203
	s_nop 1
	s_and_b64 s[16:17], vcc, exec
	s_cbranch_scc1 .LBB0_40
	v_lshl_add_u64 v[204:205], s[76:77], 0, v[4:5]
	global_load_dwordx4 v[146:149], v[204:205], off
	global_load_dwordx4 v[150:153], v[204:205], off offset:16
	v_lshl_add_u64 v[204:205], s[78:79], 0, v[4:5]
	global_load_dwordx4 v[154:157], v[204:205], off
	global_load_dwordx4 v[158:161], v[204:205], off offset:16
	v_lshl_add_u64 v[206:207], v[4:5], 0, s[10:11]
	v_lshl_add_u64 v[204:205], s[76:77], 0, v[206:207]
	global_load_dwordx4 v[162:165], v[204:205], off
	global_load_dwordx4 v[166:169], v[204:205], off offset:16
	v_lshl_add_u64 v[204:205], s[78:79], 0, v[206:207]
	global_load_dwordx4 v[170:173], v[204:205], off
	global_load_dwordx4 v[174:177], v[204:205], off offset:16
	v_ashrrev_i32_e32 v18, 14, v2
	v_bfe_u32 v20, v2, 3, 3
	v_and_or_b32 v18, v18, s1, v20
	v_mul_i32_i24_e32 v18, 0x820, v18
	v_bfe_u32 v6, v2, 6, 11
	v_ashrrev_i32_e32 v19, 31, v18
	v_lshl_add_u64 v[18:19], v[18:19], 0, v[6:7]
	v_lshlrev_b64 v[198:199], 7, v[18:19]
	v_ashrrev_i32_e32 v18, 14, v203
	v_bfe_u32 v20, v203, 3, 3
	v_and_or_b32 v18, v18, s1, v20
	v_mul_i32_i24_e32 v18, 0x820, v18
	v_bfe_u32 v6, v203, 6, 11
	v_ashrrev_i32_e32 v19, 31, v18
	v_lshl_add_u64 v[18:19], v[18:19], 0, v[6:7]
	v_lshlrev_b64 v[200:201], 7, v[18:19]
	v_and_b32_e32 v6, 56, v1
	v_lshlrev_b32_e32 v6, 1, v6
	v_lshl_add_u64 v[198:199], v[198:199], 0, v[6:7]
	v_lshl_add_u64 v[200:201], v[200:201], 0, v[6:7]
	v_add_u32_e32 v2, s0, v203
	v_add_u32_e32 v1, s3, v1
	v_add_u32_e32 v1, s3, v1
	v_lshl_add_u64 v[4:5], v[206:207], 0, s[10:11]
	s_waitcnt vmcnt(6)
	v_cvt_pk_bf16_f32 v146, v146, v147
	v_cvt_pk_bf16_f32 v147, v148, v149
	v_cvt_pk_bf16_f32 v148, v150, v151
	v_cvt_pk_bf16_f32 v149, v152, v153
	v_lshl_add_u64 v[204:205], s[6:7], 0, v[198:199]
	global_store_dwordx4 v[204:205], v[146:149], off
	s_waitcnt vmcnt(5)
	v_cvt_pk_bf16_f32 v154, v154, v155
	v_cvt_pk_bf16_f32 v155, v156, v157
	v_cvt_pk_bf16_f32 v156, v158, v159
	v_cvt_pk_bf16_f32 v157, v160, v161
	v_lshl_add_u64 v[204:205], s[8:9], 0, v[198:199]
	global_store_dwordx4 v[204:205], v[154:157], off
	s_waitcnt vmcnt(4)
	v_cvt_pk_bf16_f32 v162, v162, v163
	v_cvt_pk_bf16_f32 v163, v164, v165
	v_cvt_pk_bf16_f32 v164, v166, v167
	v_cvt_pk_bf16_f32 v165, v168, v169
	v_lshl_add_u64 v[204:205], s[6:7], 0, v[200:201]
	global_store_dwordx4 v[204:205], v[162:165], off
	s_waitcnt vmcnt(3)
	v_cvt_pk_bf16_f32 v170, v170, v171
	v_cvt_pk_bf16_f32 v171, v172, v173
	v_cvt_pk_bf16_f32 v172, v174, v175
	v_cvt_pk_bf16_f32 v173, v176, v177
	v_lshl_add_u64 v[204:205], s[8:9], 0, v[200:201]
	global_store_dwordx4 v[204:205], v[170:173], off
	v_cmp_lt_i32_e32 vcc, s14, v2
	s_nop 1
	s_andn2_b64 s[16:17], exec, vcc
	s_cbranch_scc0 .LBB0_41
	s_mov_b64 exec, s[16:17]
	s_branch .Lcvb_top
